# P6: residual h1 folded into the accumulators inside the K loop (one item per trip, loads overlapped with MFMA), store-only epilogue
# speedup vs baseline: 1.0336x; 1.0043x over previous
; __device__ __forceinline__ float bflo(unsigned w) { return __uint_as_float(w << 16); }
; __device__ __forceinline__ float bfhi(unsigned w) { return __uint_as_float(w & 0xffff0000u); }
; #define PG8_WAIT_V(n) asm volatile("s_waitcnt vmcnt(" #n ")" ::: "memory")
; #define PG8_WAIT_L(n) asm volatile("s_waitcnt lgkmcnt(" #n ")" ::: "memory")
; #define PG8_BAR __builtin_amdgcn_s_barrier()
; template <class Epi, class Sched, bool ALIGN_EPI>
; __device__ __forceinline__ void gemm_phase(PG8_LAS unsigned char* lds, const Gemm g, const Sched& S, const Epi& E) {
;     ...
;         for (int t = 0; t < nt; t += 2) {
;             const bool last = (t == nt - 2);
;             const char* a1 = cA + (size_t)(t + 1) * kstep;
;             const char* a2 = last ? nA : cA + (size_t)(t + 2) * kstep; const char* b2 = last ? nB : cB + (size_t)(t + 2) * kstep;
;             const char* a3 = a2 + kstep; const char* b3 = b2 + kstep;
;             if constexpr (Epi::MID_T >= 0) { if (t == Epi::MID_T) E.mid(acc, cur, wr, fr); }
;             PG8_LDB(B0, 0, 0); PG8_LDB(B1, 0, 1); PG8_SCHED; PG8_LDA(At, 0, 0); PG8_STAGE(PG8_SA(1, 1), a1 + hsA, voffA);
;             PG8_WAIT_V(8); PG8_WAIT_L(0); PG8_BAR; PG8_MMA(0, 0, At, B0); PG8_MMA(0, 1, At, B1); PG8_BAR; PG8_SCHED;
;     __device__ __forceinline__ void operator()(const f32x4 (&acc)[2][2][4][2], const Unit& u, int wr, int wc, int fr, int fq) const {
;     ...
;             for (int m = 0; m < 4; ++m) { const int row = row0 + ai * HALF + m * 16;
; #pragma unroll
;                 for (int bj = 0; bj < 2; ++bj) { const size_t off = (size_t)row * DM + u.pn * BM + bj * HALF + wc * 32 + 8 * fq;
;                     const u32x4 hw = *(const u32x4*)(H1B + off), lw = *(const u32x4*)(LO + off);
;                     f32x4 o0, o1;
;                     o0[0] = (bflo(hw.x) + bflo(lw.x)) + acc[ai][bj][m][0][0]; o0[1] = (bfhi(hw.x) + bfhi(lw.x)) + acc[ai][bj][m][0][1];
;                     o0[2] = (bflo(hw.y) + bflo(lw.y)) + acc[ai][bj][m][0][2]; o0[3] = (bfhi(hw.y) + bfhi(lw.y)) + acc[ai][bj][m][0][3];
;                     o1[0] = (bflo(hw.z) + bflo(lw.z)) + acc[ai][bj][m][1][0]; o1[1] = (bfhi(hw.z) + bfhi(lw.z)) + acc[ai][bj][m][1][1];
;                     o1[2] = (bflo(hw.w) + bflo(lw.w)) + acc[ai][bj][m][1][2]; o1[3] = (bfhi(hw.w) + bfhi(lw.w)) + acc[ai][bj][m][1][3];
;                     *(f32x4*)(out + off) = o0; *(f32x4*)(out + off + 4) = o1; } }
.LBB0_1025:
	ds_read_b128 v[152:155], v149
	ds_read_b128 v[156:159], v149 offset:1024
	ds_read_b128 v[160:163], v149 offset:2048
	ds_read_b128 v[164:167], v149 offset:3072
	ds_read_b128 v[168:171], v150
	ds_read_b128 v[172:175], v150 offset:1024
	ds_read_b128 v[176:179], v150 offset:2048
	ds_read_b128 v[180:183], v150 offset:3072
	s_add_u32 s40, s38, 0xfff50080
	s_addc_u32 s41, s39, -1
	s_cmp_eq_u32 s63, 40
	s_cselect_b32 s43, s3, s41
	s_cselect_b32 s42, s2, s40
	s_cselect_b32 s41, s37, s62
	s_cselect_b32 s40, s36, s61
	v_lshl_add_u64 v[146:147], s[38:39], 0, v[138:139]
	s_add_i32 m0, s47, 0xc000
	ds_read_b128 v[184:187], v151
	ds_read_b128 v[188:191], v151 offset:1024
	ds_read_b128 v[192:195], v151 offset:2048
	ds_read_b128 v[196:199], v151 offset:3072
	ds_read_b128 v[200:203], v151 offset:4096
	ds_read_b128 v[204:207], v151 offset:5120
	ds_read_b128 v[208:211], v151 offset:6144
	ds_read_b128 v[212:215], v151 offset:7168
	global_load_lds_dwordx4 v[146:147], off
	v_lshl_add_u64 v[146:147], s[38:39], 0, v[140:141]
	s_add_i32 m0, s47, 0xe000
	s_nop 0
	global_load_lds_dwordx4 v[146:147], off
	s_add_i32 vcc_lo, s63, 2
	s_cmp_gt_u32 vcc_lo, 32
	s_cbranch_scc1 .Lp6h_dummy
	s_cmp_eq_u32 vcc_lo, 0
	s_cbranch_scc1 .Lp6h_0
	s_cmp_eq_u32 vcc_lo, 2
	s_cbranch_scc1 .Lp6h_1
	s_cmp_eq_u32 vcc_lo, 4
	s_cbranch_scc1 .Lp6h_2
	s_cmp_eq_u32 vcc_lo, 6
	s_cbranch_scc1 .Lp6h_3
	s_cmp_eq_u32 vcc_lo, 8
	s_cbranch_scc1 .Lp6h_4
	s_cmp_eq_u32 vcc_lo, 10
	s_cbranch_scc1 .Lp6h_5
	s_cmp_eq_u32 vcc_lo, 12
	s_cbranch_scc1 .Lp6h_6
	s_cmp_eq_u32 vcc_lo, 14
	s_cbranch_scc1 .Lp6h_7
	s_cmp_eq_u32 vcc_lo, 16
	s_cbranch_scc1 .Lp6h_8
	s_cmp_eq_u32 vcc_lo, 18
	s_cbranch_scc1 .Lp6h_9
	s_cmp_eq_u32 vcc_lo, 20
	s_cbranch_scc1 .Lp6h_10
	s_cmp_eq_u32 vcc_lo, 22
	s_cbranch_scc1 .Lp6h_11
	s_cmp_eq_u32 vcc_lo, 24
	s_cbranch_scc1 .Lp6h_12
	s_cmp_eq_u32 vcc_lo, 26
	s_cbranch_scc1 .Lp6h_13
	s_cmp_eq_u32 vcc_lo, 28
	s_cbranch_scc1 .Lp6h_14
	s_cmp_eq_u32 vcc_lo, 30
	s_cbranch_scc1 .Lp6h_15
	s_cmp_eq_u32 vcc_lo, 32
	s_cbranch_scc1 .Lp6h_16
	s_branch .Lp6h_dummy
.Lp6h_0:
	s_lshl_b32 vcc_lo, s59, 19
	s_lshl_b32 vcc_hi, s60, 9
	s_add_i32 vcc_lo, vcc_lo, vcc_hi
	s_add_u32 s98, s6, vcc_lo
	s_addc_u32 s99, s7, 0
	s_add_u32 s100, s8, vcc_lo
	s_addc_u32 s101, s9, 0
	v_lshl_add_u32 v240, v137, 10, v136
	v_lshlrev_b32_e32 v240, 1, v240
	global_load_dwordx4 v[224:227], v240, s[98:99]
	global_load_dwordx4 v[228:231], v240, s[100:101]
	s_branch .Lp6h_ret
.Lp6h_1:
	s_nop 3
	v_lshlrev_b32_e32 v240, 16, v224
	v_and_b32_e32 v241, 0xffff0000, v224
	v_lshlrev_b32_e32 v242, 16, v228
	v_and_b32_e32 v243, 0xffff0000, v228
	v_pk_add_f32 v[240:241], v[240:241], v[242:243]
	v_pk_add_f32 v[124:125], v[124:125], v[240:241]
	v_lshlrev_b32_e32 v240, 16, v225
	v_and_b32_e32 v241, 0xffff0000, v225
	v_lshlrev_b32_e32 v242, 16, v229
	v_and_b32_e32 v243, 0xffff0000, v229
	v_pk_add_f32 v[240:241], v[240:241], v[242:243]
	v_pk_add_f32 v[126:127], v[126:127], v[240:241]
	v_lshlrev_b32_e32 v240, 16, v226
	v_and_b32_e32 v241, 0xffff0000, v226
	v_lshlrev_b32_e32 v242, 16, v230
	v_and_b32_e32 v243, 0xffff0000, v230
	v_pk_add_f32 v[240:241], v[240:241], v[242:243]
	v_pk_add_f32 v[120:121], v[120:121], v[240:241]
	v_lshlrev_b32_e32 v240, 16, v227
	v_and_b32_e32 v241, 0xffff0000, v227
	v_lshlrev_b32_e32 v242, 16, v231
	v_and_b32_e32 v243, 0xffff0000, v231
	v_pk_add_f32 v[240:241], v[240:241], v[242:243]
	v_pk_add_f32 v[122:123], v[122:123], v[240:241]
	v_lshl_add_u32 v240, v137, 10, v136
	v_lshlrev_b32_e32 v240, 1, v240
	global_load_dwordx4 v[232:235], v240, s[98:99] offset:256
	global_load_dwordx4 v[236:239], v240, s[100:101] offset:256
	s_branch .Lp6h_ret
.Lp6h_2:
	s_nop 3
	v_lshlrev_b32_e32 v240, 16, v232
	v_and_b32_e32 v241, 0xffff0000, v232
	v_lshlrev_b32_e32 v242, 16, v236
	v_and_b32_e32 v243, 0xffff0000, v236
	v_pk_add_f32 v[240:241], v[240:241], v[242:243]
	v_pk_add_f32 v[116:117], v[116:117], v[240:241]
	v_lshlrev_b32_e32 v240, 16, v233
	v_and_b32_e32 v241, 0xffff0000, v233
	v_lshlrev_b32_e32 v242, 16, v237
	v_and_b32_e32 v243, 0xffff0000, v237
	v_pk_add_f32 v[240:241], v[240:241], v[242:243]
	v_pk_add_f32 v[118:119], v[118:119], v[240:241]
	v_lshlrev_b32_e32 v240, 16, v234
	v_and_b32_e32 v241, 0xffff0000, v234
	v_lshlrev_b32_e32 v242, 16, v238
	v_and_b32_e32 v243, 0xffff0000, v238
	v_pk_add_f32 v[240:241], v[240:241], v[242:243]
	v_pk_add_f32 v[112:113], v[112:113], v[240:241]
	v_lshlrev_b32_e32 v240, 16, v235
	v_and_b32_e32 v241, 0xffff0000, v235
	v_lshlrev_b32_e32 v242, 16, v239
	v_and_b32_e32 v243, 0xffff0000, v239
	v_pk_add_f32 v[240:241], v[240:241], v[242:243]
	v_pk_add_f32 v[114:115], v[114:115], v[240:241]
	s_lshl_b32 vcc_lo, s59, 19
	s_lshl_b32 vcc_hi, s60, 9
	s_add_i32 vcc_lo, vcc_lo, vcc_hi
	s_add_i32 vcc_lo, vcc_lo, 0x8000
	s_add_u32 s98, s6, vcc_lo
	s_addc_u32 s99, s7, 0
	s_add_u32 s100, s8, vcc_lo
	s_addc_u32 s101, s9, 0
	v_lshl_add_u32 v240, v137, 10, v136
	v_lshlrev_b32_e32 v240, 1, v240
	global_load_dwordx4 v[224:227], v240, s[98:99]
	global_load_dwordx4 v[228:231], v240, s[100:101]
	s_branch .Lp6h_ret
.Lp6h_3:
	s_nop 3
	v_lshlrev_b32_e32 v240, 16, v224
	v_and_b32_e32 v241, 0xffff0000, v224
	v_lshlrev_b32_e32 v242, 16, v228
	v_and_b32_e32 v243, 0xffff0000, v228
	v_pk_add_f32 v[240:241], v[240:241], v[242:243]
	v_pk_add_f32 v[108:109], v[108:109], v[240:241]
	v_lshlrev_b32_e32 v240, 16, v225
	v_and_b32_e32 v241, 0xffff0000, v225
	v_lshlrev_b32_e32 v242, 16, v229
	v_and_b32_e32 v243, 0xffff0000, v229
	v_pk_add_f32 v[240:241], v[240:241], v[242:243]
	v_pk_add_f32 v[110:111], v[110:111], v[240:241]
	v_lshlrev_b32_e32 v240, 16, v226
	v_and_b32_e32 v241, 0xffff0000, v226
	v_lshlrev_b32_e32 v242, 16, v230
	v_and_b32_e32 v243, 0xffff0000, v230
	v_pk_add_f32 v[240:241], v[240:241], v[242:243]
	v_pk_add_f32 v[104:105], v[104:105], v[240:241]
	v_lshlrev_b32_e32 v240, 16, v227
	v_and_b32_e32 v241, 0xffff0000, v227
	v_lshlrev_b32_e32 v242, 16, v231
	v_and_b32_e32 v243, 0xffff0000, v231
	v_pk_add_f32 v[240:241], v[240:241], v[242:243]
	v_pk_add_f32 v[106:107], v[106:107], v[240:241]
	v_lshl_add_u32 v240, v137, 10, v136
	v_lshlrev_b32_e32 v240, 1, v240
	global_load_dwordx4 v[232:235], v240, s[98:99] offset:256
	global_load_dwordx4 v[236:239], v240, s[100:101] offset:256
	s_branch .Lp6h_ret
; __device__ __forceinline__ float bflo(unsigned w) { return __uint_as_float(w << 16); }
; __device__ __forceinline__ float bfhi(unsigned w) { return __uint_as_float(w & 0xffff0000u); }
;     __device__ __forceinline__ void operator()(const f32x4 (&acc)[2][2][4][2], const Unit& u, int wr, int wc, int fr, int fq) const {
;     ...
;             for (int m = 0; m < 4; ++m) { const int row = row0 + ai * HALF + m * 16;
; #pragma unroll
;                 for (int bj = 0; bj < 2; ++bj) { const size_t off = (size_t)row * DM + u.pn * BM + bj * HALF + wc * 32 + 8 * fq;
;                     const u32x4 hw = *(const u32x4*)(H1B + off), lw = *(const u32x4*)(LO + off);
;                     f32x4 o0, o1;
;                     o0[0] = (bflo(hw.x) + bflo(lw.x)) + acc[ai][bj][m][0][0]; o0[1] = (bfhi(hw.x) + bfhi(lw.x)) + acc[ai][bj][m][0][1];
;                     o0[2] = (bflo(hw.y) + bflo(lw.y)) + acc[ai][bj][m][0][2]; o0[3] = (bfhi(hw.y) + bfhi(lw.y)) + acc[ai][bj][m][0][3];
;                     o1[0] = (bflo(hw.z) + bflo(lw.z)) + acc[ai][bj][m][1][0]; o1[1] = (bfhi(hw.z) + bfhi(lw.z)) + acc[ai][bj][m][1][1];
;                     o1[2] = (bflo(hw.w) + bflo(lw.w)) + acc[ai][bj][m][1][2]; o1[3] = (bfhi(hw.w) + bfhi(lw.w)) + acc[ai][bj][m][1][3];
;                     *(f32x4*)(out + off) = o0; *(f32x4*)(out + off + 4) = o1; } }
.Lp6h_4:
	s_nop 3
	v_lshlrev_b32_e32 v240, 16, v232
	v_and_b32_e32 v241, 0xffff0000, v232
	v_lshlrev_b32_e32 v242, 16, v236
	v_and_b32_e32 v243, 0xffff0000, v236
	v_pk_add_f32 v[240:241], v[240:241], v[242:243]
	v_pk_add_f32 v[100:101], v[100:101], v[240:241]
	v_lshlrev_b32_e32 v240, 16, v233
	v_and_b32_e32 v241, 0xffff0000, v233
	v_lshlrev_b32_e32 v242, 16, v237
	v_and_b32_e32 v243, 0xffff0000, v237
	v_pk_add_f32 v[240:241], v[240:241], v[242:243]
	v_pk_add_f32 v[102:103], v[102:103], v[240:241]
	v_lshlrev_b32_e32 v240, 16, v234
	v_and_b32_e32 v241, 0xffff0000, v234
	v_lshlrev_b32_e32 v242, 16, v238
	v_and_b32_e32 v243, 0xffff0000, v238
	v_pk_add_f32 v[240:241], v[240:241], v[242:243]
	v_pk_add_f32 v[96:97], v[96:97], v[240:241]
	v_lshlrev_b32_e32 v240, 16, v235
	v_and_b32_e32 v241, 0xffff0000, v235
	v_lshlrev_b32_e32 v242, 16, v239
	v_and_b32_e32 v243, 0xffff0000, v239
	v_pk_add_f32 v[240:241], v[240:241], v[242:243]
	v_pk_add_f32 v[98:99], v[98:99], v[240:241]
	s_lshl_b32 vcc_lo, s59, 19
	s_lshl_b32 vcc_hi, s60, 9
	s_add_i32 vcc_lo, vcc_lo, vcc_hi
	s_add_i32 vcc_lo, vcc_lo, 0x10000
	s_add_u32 s98, s6, vcc_lo
	s_addc_u32 s99, s7, 0
	s_add_u32 s100, s8, vcc_lo
	s_addc_u32 s101, s9, 0
	v_lshl_add_u32 v240, v137, 10, v136
	v_lshlrev_b32_e32 v240, 1, v240
	global_load_dwordx4 v[224:227], v240, s[98:99]
	global_load_dwordx4 v[228:231], v240, s[100:101]
	s_branch .Lp6h_ret
.Lp6h_5:
	s_nop 3
	v_lshlrev_b32_e32 v240, 16, v224
	v_and_b32_e32 v241, 0xffff0000, v224
	v_lshlrev_b32_e32 v242, 16, v228
	v_and_b32_e32 v243, 0xffff0000, v228
	v_pk_add_f32 v[240:241], v[240:241], v[242:243]
	v_pk_add_f32 v[92:93], v[92:93], v[240:241]
	v_lshlrev_b32_e32 v240, 16, v225
	v_and_b32_e32 v241, 0xffff0000, v225
	v_lshlrev_b32_e32 v242, 16, v229
	v_and_b32_e32 v243, 0xffff0000, v229
	v_pk_add_f32 v[240:241], v[240:241], v[242:243]
	v_pk_add_f32 v[94:95], v[94:95], v[240:241]
	v_lshlrev_b32_e32 v240, 16, v226
	v_and_b32_e32 v241, 0xffff0000, v226
	v_lshlrev_b32_e32 v242, 16, v230
	v_and_b32_e32 v243, 0xffff0000, v230
	v_pk_add_f32 v[240:241], v[240:241], v[242:243]
	v_pk_add_f32 v[88:89], v[88:89], v[240:241]
	v_lshlrev_b32_e32 v240, 16, v227
	v_and_b32_e32 v241, 0xffff0000, v227
	v_lshlrev_b32_e32 v242, 16, v231
	v_and_b32_e32 v243, 0xffff0000, v231
	v_pk_add_f32 v[240:241], v[240:241], v[242:243]
	v_pk_add_f32 v[90:91], v[90:91], v[240:241]
	v_lshl_add_u32 v240, v137, 10, v136
	v_lshlrev_b32_e32 v240, 1, v240
	global_load_dwordx4 v[232:235], v240, s[98:99] offset:256
	global_load_dwordx4 v[236:239], v240, s[100:101] offset:256
	s_branch .Lp6h_ret
.Lp6h_6:
	s_nop 3
	v_lshlrev_b32_e32 v240, 16, v232
	v_and_b32_e32 v241, 0xffff0000, v232
	v_lshlrev_b32_e32 v242, 16, v236
	v_and_b32_e32 v243, 0xffff0000, v236
	v_pk_add_f32 v[240:241], v[240:241], v[242:243]
	v_pk_add_f32 v[84:85], v[84:85], v[240:241]
	v_lshlrev_b32_e32 v240, 16, v233
	v_and_b32_e32 v241, 0xffff0000, v233
	v_lshlrev_b32_e32 v242, 16, v237
	v_and_b32_e32 v243, 0xffff0000, v237
	v_pk_add_f32 v[240:241], v[240:241], v[242:243]
	v_pk_add_f32 v[86:87], v[86:87], v[240:241]
	v_lshlrev_b32_e32 v240, 16, v234
	v_and_b32_e32 v241, 0xffff0000, v234
	v_lshlrev_b32_e32 v242, 16, v238
	v_and_b32_e32 v243, 0xffff0000, v238
	v_pk_add_f32 v[240:241], v[240:241], v[242:243]
	v_pk_add_f32 v[80:81], v[80:81], v[240:241]
	v_lshlrev_b32_e32 v240, 16, v235
	v_and_b32_e32 v241, 0xffff0000, v235
	v_lshlrev_b32_e32 v242, 16, v239
	v_and_b32_e32 v243, 0xffff0000, v239
	v_pk_add_f32 v[240:241], v[240:241], v[242:243]
	v_pk_add_f32 v[82:83], v[82:83], v[240:241]
	s_lshl_b32 vcc_lo, s59, 19
	s_lshl_b32 vcc_hi, s60, 9
	s_add_i32 vcc_lo, vcc_lo, vcc_hi
	s_add_i32 vcc_lo, vcc_lo, 0x18000
	s_add_u32 s98, s6, vcc_lo
	s_addc_u32 s99, s7, 0
	s_add_u32 s100, s8, vcc_lo
	s_addc_u32 s101, s9, 0
	v_lshl_add_u32 v240, v137, 10, v136
	v_lshlrev_b32_e32 v240, 1, v240
	global_load_dwordx4 v[224:227], v240, s[98:99]
	global_load_dwordx4 v[228:231], v240, s[100:101]
	s_branch .Lp6h_ret
.Lp6h_7:
	s_nop 3
	v_lshlrev_b32_e32 v240, 16, v224
	v_and_b32_e32 v241, 0xffff0000, v224
	v_lshlrev_b32_e32 v242, 16, v228
	v_and_b32_e32 v243, 0xffff0000, v228
	v_pk_add_f32 v[240:241], v[240:241], v[242:243]
	v_pk_add_f32 v[76:77], v[76:77], v[240:241]
	v_lshlrev_b32_e32 v240, 16, v225
	v_and_b32_e32 v241, 0xffff0000, v225
	v_lshlrev_b32_e32 v242, 16, v229
	v_and_b32_e32 v243, 0xffff0000, v229
	v_pk_add_f32 v[240:241], v[240:241], v[242:243]
	v_pk_add_f32 v[78:79], v[78:79], v[240:241]
	v_lshlrev_b32_e32 v240, 16, v226
	v_and_b32_e32 v241, 0xffff0000, v226
	v_lshlrev_b32_e32 v242, 16, v230
	v_and_b32_e32 v243, 0xffff0000, v230
	v_pk_add_f32 v[240:241], v[240:241], v[242:243]
	v_pk_add_f32 v[72:73], v[72:73], v[240:241]
	v_lshlrev_b32_e32 v240, 16, v227
	v_and_b32_e32 v241, 0xffff0000, v227
	v_lshlrev_b32_e32 v242, 16, v231
	v_and_b32_e32 v243, 0xffff0000, v231
	v_pk_add_f32 v[240:241], v[240:241], v[242:243]
	v_pk_add_f32 v[74:75], v[74:75], v[240:241]
	v_lshl_add_u32 v240, v137, 10, v136
	v_lshlrev_b32_e32 v240, 1, v240
	global_load_dwordx4 v[232:235], v240, s[98:99] offset:256
	global_load_dwordx4 v[236:239], v240, s[100:101] offset:256
	s_branch .Lp6h_ret
; __device__ __forceinline__ float bflo(unsigned w) { return __uint_as_float(w << 16); }
; __device__ __forceinline__ float bfhi(unsigned w) { return __uint_as_float(w & 0xffff0000u); }
;     __device__ __forceinline__ void operator()(const f32x4 (&acc)[2][2][4][2], const Unit& u, int wr, int wc, int fr, int fq) const {
;     ...
;             for (int m = 0; m < 4; ++m) { const int row = row0 + ai * HALF + m * 16;
; #pragma unroll
;                 for (int bj = 0; bj < 2; ++bj) { const size_t off = (size_t)row * DM + u.pn * BM + bj * HALF + wc * 32 + 8 * fq;
;                     const u32x4 hw = *(const u32x4*)(H1B + off), lw = *(const u32x4*)(LO + off);
;                     f32x4 o0, o1;
;                     o0[0] = (bflo(hw.x) + bflo(lw.x)) + acc[ai][bj][m][0][0]; o0[1] = (bfhi(hw.x) + bfhi(lw.x)) + acc[ai][bj][m][0][1];
;                     o0[2] = (bflo(hw.y) + bflo(lw.y)) + acc[ai][bj][m][0][2]; o0[3] = (bfhi(hw.y) + bfhi(lw.y)) + acc[ai][bj][m][0][3];
;                     o1[0] = (bflo(hw.z) + bflo(lw.z)) + acc[ai][bj][m][1][0]; o1[1] = (bfhi(hw.z) + bfhi(lw.z)) + acc[ai][bj][m][1][1];
;                     o1[2] = (bflo(hw.w) + bflo(lw.w)) + acc[ai][bj][m][1][2]; o1[3] = (bfhi(hw.w) + bfhi(lw.w)) + acc[ai][bj][m][1][3];
;                     *(f32x4*)(out + off) = o0; *(f32x4*)(out + off + 4) = o1; } }
.Lp6h_8:
	s_nop 3
	v_lshlrev_b32_e32 v240, 16, v232
	v_and_b32_e32 v241, 0xffff0000, v232
	v_lshlrev_b32_e32 v242, 16, v236
	v_and_b32_e32 v243, 0xffff0000, v236
	v_pk_add_f32 v[240:241], v[240:241], v[242:243]
	v_pk_add_f32 v[68:69], v[68:69], v[240:241]
	v_lshlrev_b32_e32 v240, 16, v233
	v_and_b32_e32 v241, 0xffff0000, v233
	v_lshlrev_b32_e32 v242, 16, v237
	v_and_b32_e32 v243, 0xffff0000, v237
	v_pk_add_f32 v[240:241], v[240:241], v[242:243]
	v_pk_add_f32 v[70:71], v[70:71], v[240:241]
	v_lshlrev_b32_e32 v240, 16, v234
	v_and_b32_e32 v241, 0xffff0000, v234
	v_lshlrev_b32_e32 v242, 16, v238
	v_and_b32_e32 v243, 0xffff0000, v238
	v_pk_add_f32 v[240:241], v[240:241], v[242:243]
	v_pk_add_f32 v[64:65], v[64:65], v[240:241]
	v_lshlrev_b32_e32 v240, 16, v235
	v_and_b32_e32 v241, 0xffff0000, v235
	v_lshlrev_b32_e32 v242, 16, v239
	v_and_b32_e32 v243, 0xffff0000, v239
	v_pk_add_f32 v[240:241], v[240:241], v[242:243]
	v_pk_add_f32 v[66:67], v[66:67], v[240:241]
	s_lshl_b32 vcc_lo, s59, 19
	s_lshl_b32 vcc_hi, s60, 9
	s_add_i32 vcc_lo, vcc_lo, vcc_hi
	s_add_i32 vcc_lo, vcc_lo, 0x40000
	s_add_u32 s98, s6, vcc_lo
	s_addc_u32 s99, s7, 0
	s_add_u32 s100, s8, vcc_lo
	s_addc_u32 s101, s9, 0
	v_lshl_add_u32 v240, v137, 10, v136
	v_lshlrev_b32_e32 v240, 1, v240
	global_load_dwordx4 v[224:227], v240, s[98:99]
	global_load_dwordx4 v[228:231], v240, s[100:101]
	s_branch .Lp6h_ret
.Lp6h_9:
	s_nop 3
	v_lshlrev_b32_e32 v240, 16, v224
	v_and_b32_e32 v241, 0xffff0000, v224
	v_lshlrev_b32_e32 v242, 16, v228
	v_and_b32_e32 v243, 0xffff0000, v228
	v_pk_add_f32 v[240:241], v[240:241], v[242:243]
	v_pk_add_f32 v[60:61], v[60:61], v[240:241]
	v_lshlrev_b32_e32 v240, 16, v225
	v_and_b32_e32 v241, 0xffff0000, v225
	v_lshlrev_b32_e32 v242, 16, v229
	v_and_b32_e32 v243, 0xffff0000, v229
	v_pk_add_f32 v[240:241], v[240:241], v[242:243]
	v_pk_add_f32 v[62:63], v[62:63], v[240:241]
	v_lshlrev_b32_e32 v240, 16, v226
	v_and_b32_e32 v241, 0xffff0000, v226
	v_lshlrev_b32_e32 v242, 16, v230
	v_and_b32_e32 v243, 0xffff0000, v230
	v_pk_add_f32 v[240:241], v[240:241], v[242:243]
	v_pk_add_f32 v[56:57], v[56:57], v[240:241]
	v_lshlrev_b32_e32 v240, 16, v227
	v_and_b32_e32 v241, 0xffff0000, v227
	v_lshlrev_b32_e32 v242, 16, v231
	v_and_b32_e32 v243, 0xffff0000, v231
	v_pk_add_f32 v[240:241], v[240:241], v[242:243]
	v_pk_add_f32 v[58:59], v[58:59], v[240:241]
	v_lshl_add_u32 v240, v137, 10, v136
	v_lshlrev_b32_e32 v240, 1, v240
	global_load_dwordx4 v[232:235], v240, s[98:99] offset:256
	global_load_dwordx4 v[236:239], v240, s[100:101] offset:256
	s_branch .Lp6h_ret
.Lp6h_10:
	s_nop 3
	v_lshlrev_b32_e32 v240, 16, v232
	v_and_b32_e32 v241, 0xffff0000, v232
	v_lshlrev_b32_e32 v242, 16, v236
	v_and_b32_e32 v243, 0xffff0000, v236
	v_pk_add_f32 v[240:241], v[240:241], v[242:243]
	v_pk_add_f32 v[52:53], v[52:53], v[240:241]
	v_lshlrev_b32_e32 v240, 16, v233
	v_and_b32_e32 v241, 0xffff0000, v233
	v_lshlrev_b32_e32 v242, 16, v237
	v_and_b32_e32 v243, 0xffff0000, v237
	v_pk_add_f32 v[240:241], v[240:241], v[242:243]
	v_pk_add_f32 v[54:55], v[54:55], v[240:241]
	v_lshlrev_b32_e32 v240, 16, v234
	v_and_b32_e32 v241, 0xffff0000, v234
	v_lshlrev_b32_e32 v242, 16, v238
	v_and_b32_e32 v243, 0xffff0000, v238
	v_pk_add_f32 v[240:241], v[240:241], v[242:243]
	v_pk_add_f32 v[48:49], v[48:49], v[240:241]
	v_lshlrev_b32_e32 v240, 16, v235
	v_and_b32_e32 v241, 0xffff0000, v235
	v_lshlrev_b32_e32 v242, 16, v239
	v_and_b32_e32 v243, 0xffff0000, v239
	v_pk_add_f32 v[240:241], v[240:241], v[242:243]
	v_pk_add_f32 v[50:51], v[50:51], v[240:241]
	s_lshl_b32 vcc_lo, s59, 19
	s_lshl_b32 vcc_hi, s60, 9
	s_add_i32 vcc_lo, vcc_lo, vcc_hi
	s_add_i32 vcc_lo, vcc_lo, 0x48000
	s_add_u32 s98, s6, vcc_lo
	s_addc_u32 s99, s7, 0
	s_add_u32 s100, s8, vcc_lo
	s_addc_u32 s101, s9, 0
	v_lshl_add_u32 v240, v137, 10, v136
	v_lshlrev_b32_e32 v240, 1, v240
	global_load_dwordx4 v[224:227], v240, s[98:99]
	global_load_dwordx4 v[228:231], v240, s[100:101]
	s_branch .Lp6h_ret
.Lp6h_11:
	s_nop 3
	v_lshlrev_b32_e32 v240, 16, v224
	v_and_b32_e32 v241, 0xffff0000, v224
	v_lshlrev_b32_e32 v242, 16, v228
	v_and_b32_e32 v243, 0xffff0000, v228
	v_pk_add_f32 v[240:241], v[240:241], v[242:243]
	v_pk_add_f32 v[44:45], v[44:45], v[240:241]
	v_lshlrev_b32_e32 v240, 16, v225
	v_and_b32_e32 v241, 0xffff0000, v225
	v_lshlrev_b32_e32 v242, 16, v229
	v_and_b32_e32 v243, 0xffff0000, v229
	v_pk_add_f32 v[240:241], v[240:241], v[242:243]
	v_pk_add_f32 v[46:47], v[46:47], v[240:241]
	v_lshlrev_b32_e32 v240, 16, v226
	v_and_b32_e32 v241, 0xffff0000, v226
	v_lshlrev_b32_e32 v242, 16, v230
	v_and_b32_e32 v243, 0xffff0000, v230
	v_pk_add_f32 v[240:241], v[240:241], v[242:243]
	v_pk_add_f32 v[40:41], v[40:41], v[240:241]
	v_lshlrev_b32_e32 v240, 16, v227
	v_and_b32_e32 v241, 0xffff0000, v227
	v_lshlrev_b32_e32 v242, 16, v231
	v_and_b32_e32 v243, 0xffff0000, v231
	v_pk_add_f32 v[240:241], v[240:241], v[242:243]
	v_pk_add_f32 v[42:43], v[42:43], v[240:241]
	v_lshl_add_u32 v240, v137, 10, v136
	v_lshlrev_b32_e32 v240, 1, v240
	global_load_dwordx4 v[232:235], v240, s[98:99] offset:256
	global_load_dwordx4 v[236:239], v240, s[100:101] offset:256
	s_branch .Lp6h_ret
; __device__ __forceinline__ float bflo(unsigned w) { return __uint_as_float(w << 16); }
; __device__ __forceinline__ float bfhi(unsigned w) { return __uint_as_float(w & 0xffff0000u); }
;     __device__ __forceinline__ void operator()(const f32x4 (&acc)[2][2][4][2], const Unit& u, int wr, int wc, int fr, int fq) const {
;     ...
;             for (int m = 0; m < 4; ++m) { const int row = row0 + ai * HALF + m * 16;
; #pragma unroll
;                 for (int bj = 0; bj < 2; ++bj) { const size_t off = (size_t)row * DM + u.pn * BM + bj * HALF + wc * 32 + 8 * fq;
;                     const u32x4 hw = *(const u32x4*)(H1B + off), lw = *(const u32x4*)(LO + off);
;                     f32x4 o0, o1;
;                     o0[0] = (bflo(hw.x) + bflo(lw.x)) + acc[ai][bj][m][0][0]; o0[1] = (bfhi(hw.x) + bfhi(lw.x)) + acc[ai][bj][m][0][1];
;                     o0[2] = (bflo(hw.y) + bflo(lw.y)) + acc[ai][bj][m][0][2]; o0[3] = (bfhi(hw.y) + bfhi(lw.y)) + acc[ai][bj][m][0][3];
;                     o1[0] = (bflo(hw.z) + bflo(lw.z)) + acc[ai][bj][m][1][0]; o1[1] = (bfhi(hw.z) + bfhi(lw.z)) + acc[ai][bj][m][1][1];
;                     o1[2] = (bflo(hw.w) + bflo(lw.w)) + acc[ai][bj][m][1][2]; o1[3] = (bfhi(hw.w) + bfhi(lw.w)) + acc[ai][bj][m][1][3];
;                     *(f32x4*)(out + off) = o0; *(f32x4*)(out + off + 4) = o1; } }
.Lp6h_12:
	s_nop 3
	v_lshlrev_b32_e32 v240, 16, v232
	v_and_b32_e32 v241, 0xffff0000, v232
	v_lshlrev_b32_e32 v242, 16, v236
	v_and_b32_e32 v243, 0xffff0000, v236
	v_pk_add_f32 v[240:241], v[240:241], v[242:243]
	v_pk_add_f32 v[36:37], v[36:37], v[240:241]
	v_lshlrev_b32_e32 v240, 16, v233
	v_and_b32_e32 v241, 0xffff0000, v233
	v_lshlrev_b32_e32 v242, 16, v237
	v_and_b32_e32 v243, 0xffff0000, v237
	v_pk_add_f32 v[240:241], v[240:241], v[242:243]
	v_pk_add_f32 v[38:39], v[38:39], v[240:241]
	v_lshlrev_b32_e32 v240, 16, v234
	v_and_b32_e32 v241, 0xffff0000, v234
	v_lshlrev_b32_e32 v242, 16, v238
	v_and_b32_e32 v243, 0xffff0000, v238
	v_pk_add_f32 v[240:241], v[240:241], v[242:243]
	v_pk_add_f32 v[32:33], v[32:33], v[240:241]
	v_lshlrev_b32_e32 v240, 16, v235
	v_and_b32_e32 v241, 0xffff0000, v235
	v_lshlrev_b32_e32 v242, 16, v239
	v_and_b32_e32 v243, 0xffff0000, v239
	v_pk_add_f32 v[240:241], v[240:241], v[242:243]
	v_pk_add_f32 v[34:35], v[34:35], v[240:241]
	s_lshl_b32 vcc_lo, s59, 19
	s_lshl_b32 vcc_hi, s60, 9
	s_add_i32 vcc_lo, vcc_lo, vcc_hi
	s_add_i32 vcc_lo, vcc_lo, 0x50000
	s_add_u32 s98, s6, vcc_lo
	s_addc_u32 s99, s7, 0
	s_add_u32 s100, s8, vcc_lo
	s_addc_u32 s101, s9, 0
	v_lshl_add_u32 v240, v137, 10, v136
	v_lshlrev_b32_e32 v240, 1, v240
	global_load_dwordx4 v[224:227], v240, s[98:99]
	global_load_dwordx4 v[228:231], v240, s[100:101]
	s_branch .Lp6h_ret
.Lp6h_13:
	s_nop 3
	v_lshlrev_b32_e32 v240, 16, v224
	v_and_b32_e32 v241, 0xffff0000, v224
	v_lshlrev_b32_e32 v242, 16, v228
	v_and_b32_e32 v243, 0xffff0000, v228
	v_pk_add_f32 v[240:241], v[240:241], v[242:243]
	v_pk_add_f32 v[28:29], v[28:29], v[240:241]
	v_lshlrev_b32_e32 v240, 16, v225
	v_and_b32_e32 v241, 0xffff0000, v225
	v_lshlrev_b32_e32 v242, 16, v229
	v_and_b32_e32 v243, 0xffff0000, v229
	v_pk_add_f32 v[240:241], v[240:241], v[242:243]
	v_pk_add_f32 v[30:31], v[30:31], v[240:241]
	v_lshlrev_b32_e32 v240, 16, v226
	v_and_b32_e32 v241, 0xffff0000, v226
	v_lshlrev_b32_e32 v242, 16, v230
	v_and_b32_e32 v243, 0xffff0000, v230
	v_pk_add_f32 v[240:241], v[240:241], v[242:243]
	v_pk_add_f32 v[24:25], v[24:25], v[240:241]
	v_lshlrev_b32_e32 v240, 16, v227
	v_and_b32_e32 v241, 0xffff0000, v227
	v_lshlrev_b32_e32 v242, 16, v231
	v_and_b32_e32 v243, 0xffff0000, v231
	v_pk_add_f32 v[240:241], v[240:241], v[242:243]
	v_pk_add_f32 v[26:27], v[26:27], v[240:241]
	v_lshl_add_u32 v240, v137, 10, v136
	v_lshlrev_b32_e32 v240, 1, v240
	global_load_dwordx4 v[232:235], v240, s[98:99] offset:256
	global_load_dwordx4 v[236:239], v240, s[100:101] offset:256
	s_branch .Lp6h_ret
.Lp6h_14:
	s_nop 3
	v_lshlrev_b32_e32 v240, 16, v232
	v_and_b32_e32 v241, 0xffff0000, v232
	v_lshlrev_b32_e32 v242, 16, v236
	v_and_b32_e32 v243, 0xffff0000, v236
	v_pk_add_f32 v[240:241], v[240:241], v[242:243]
	v_pk_add_f32 v[20:21], v[20:21], v[240:241]
	v_lshlrev_b32_e32 v240, 16, v233
	v_and_b32_e32 v241, 0xffff0000, v233
	v_lshlrev_b32_e32 v242, 16, v237
	v_and_b32_e32 v243, 0xffff0000, v237
	v_pk_add_f32 v[240:241], v[240:241], v[242:243]
	v_pk_add_f32 v[22:23], v[22:23], v[240:241]
	v_lshlrev_b32_e32 v240, 16, v234
	v_and_b32_e32 v241, 0xffff0000, v234
	v_lshlrev_b32_e32 v242, 16, v238
	v_and_b32_e32 v243, 0xffff0000, v238
	v_pk_add_f32 v[240:241], v[240:241], v[242:243]
	v_pk_add_f32 v[16:17], v[16:17], v[240:241]
	v_lshlrev_b32_e32 v240, 16, v235
	v_and_b32_e32 v241, 0xffff0000, v235
	v_lshlrev_b32_e32 v242, 16, v239
	v_and_b32_e32 v243, 0xffff0000, v239
	v_pk_add_f32 v[240:241], v[240:241], v[242:243]
	v_pk_add_f32 v[18:19], v[18:19], v[240:241]
	s_lshl_b32 vcc_lo, s59, 19
	s_lshl_b32 vcc_hi, s60, 9
	s_add_i32 vcc_lo, vcc_lo, vcc_hi
	s_add_i32 vcc_lo, vcc_lo, 0x58000
	s_add_u32 s98, s6, vcc_lo
	s_addc_u32 s99, s7, 0
	s_add_u32 s100, s8, vcc_lo
	s_addc_u32 s101, s9, 0
	v_lshl_add_u32 v240, v137, 10, v136
	v_lshlrev_b32_e32 v240, 1, v240
	global_load_dwordx4 v[224:227], v240, s[98:99]
	global_load_dwordx4 v[228:231], v240, s[100:101]
	s_branch .Lp6h_ret
.Lp6h_15:
	s_nop 3
	v_lshlrev_b32_e32 v240, 16, v224
	v_and_b32_e32 v241, 0xffff0000, v224
	v_lshlrev_b32_e32 v242, 16, v228
	v_and_b32_e32 v243, 0xffff0000, v228
	v_pk_add_f32 v[240:241], v[240:241], v[242:243]
	v_pk_add_f32 v[12:13], v[12:13], v[240:241]
	v_lshlrev_b32_e32 v240, 16, v225
	v_and_b32_e32 v241, 0xffff0000, v225
	v_lshlrev_b32_e32 v242, 16, v229
	v_and_b32_e32 v243, 0xffff0000, v229
	v_pk_add_f32 v[240:241], v[240:241], v[242:243]
	v_pk_add_f32 v[14:15], v[14:15], v[240:241]
	v_lshlrev_b32_e32 v240, 16, v226
	v_and_b32_e32 v241, 0xffff0000, v226
	v_lshlrev_b32_e32 v242, 16, v230
	v_and_b32_e32 v243, 0xffff0000, v230
	v_pk_add_f32 v[240:241], v[240:241], v[242:243]
	v_pk_add_f32 v[8:9], v[8:9], v[240:241]
	v_lshlrev_b32_e32 v240, 16, v227
	v_and_b32_e32 v241, 0xffff0000, v227
	v_lshlrev_b32_e32 v242, 16, v231
	v_and_b32_e32 v243, 0xffff0000, v231
	v_pk_add_f32 v[240:241], v[240:241], v[242:243]
	v_pk_add_f32 v[10:11], v[10:11], v[240:241]
	v_lshl_add_u32 v240, v137, 10, v136
	v_lshlrev_b32_e32 v240, 1, v240
	global_load_dwordx4 v[232:235], v240, s[98:99] offset:256
	global_load_dwordx4 v[236:239], v240, s[100:101] offset:256
	s_branch .Lp6h_ret
; __device__ __forceinline__ float bflo(unsigned w) { return __uint_as_float(w << 16); }
; __device__ __forceinline__ float bfhi(unsigned w) { return __uint_as_float(w & 0xffff0000u); }
; #define PG8_STAGE(bufoff, gbase, voff) do { _Pragma("unroll") for (int _i = 0; _i < 2; ++_i) \
;         __builtin_amdgcn_global_load_lds((const unsigned*)((const char*)(gbase) + (voff)[_i]), (PG8_LAS unsigned*)(lds + (bufoff) + ldsw + _i * 8192), 16, 0, 0); } while (0)
; #define PG8_WAIT_V(n) asm volatile("s_waitcnt vmcnt(" #n ")" ::: "memory")
; template <class Epi, class Sched, bool ALIGN_EPI>
; __device__ __forceinline__ void gemm_phase(PG8_LAS unsigned char* lds, const Gemm g, const Sched& S, const Epi& E) {
;     ...
;             PG8_LDB(B0, 0, 0); PG8_LDB(B1, 0, 1); PG8_SCHED; PG8_LDA(At, 0, 0); PG8_STAGE(PG8_SA(1, 1), a1 + hsA, voffA);
;             PG8_WAIT_V(8); PG8_WAIT_L(0); PG8_BAR; PG8_MMA(0, 0, At, B0); PG8_MMA(0, 1, At, B1); PG8_BAR; PG8_SCHED;
;             PG8_LDA(At, 0, 1); PG8_STAGE(PG8_SB(0, 0), b2, voffB); PG8_STAGE(PG8_SB(0, 1), b2 + hsB, voffB); PG8_STAGE(PG8_SA(0, 0), a2, voffA);
;             PG8_WAIT_V(8); PG8_WAIT_L(0); PG8_BAR; PG8_MMA(1, 0, At, B0); PG8_MMA(1, 1, At, B1); PG8_BAR; PG8_SCHED;
;     __device__ __forceinline__ void operator()(const f32x4 (&acc)[2][2][4][2], const Unit& u, int wr, int wc, int fr, int fq) const {
;     ...
;             for (int m = 0; m < 4; ++m) { const int row = row0 + ai * HALF + m * 16;
; #pragma unroll
;                 for (int bj = 0; bj < 2; ++bj) { const size_t off = (size_t)row * DM + u.pn * BM + bj * HALF + wc * 32 + 8 * fq;
;                     const u32x4 hw = *(const u32x4*)(H1B + off), lw = *(const u32x4*)(LO + off);
;                     f32x4 o0, o1;
;                     o0[0] = (bflo(hw.x) + bflo(lw.x)) + acc[ai][bj][m][0][0]; o0[1] = (bfhi(hw.x) + bfhi(lw.x)) + acc[ai][bj][m][0][1];
;                     o0[2] = (bflo(hw.y) + bflo(lw.y)) + acc[ai][bj][m][0][2]; o0[3] = (bfhi(hw.y) + bfhi(lw.y)) + acc[ai][bj][m][0][3];
;                     o1[0] = (bflo(hw.z) + bflo(lw.z)) + acc[ai][bj][m][1][0]; o1[1] = (bfhi(hw.z) + bfhi(lw.z)) + acc[ai][bj][m][1][1];
;                     o1[2] = (bflo(hw.w) + bflo(lw.w)) + acc[ai][bj][m][1][2]; o1[3] = (bfhi(hw.w) + bfhi(lw.w)) + acc[ai][bj][m][1][3];
;                     *(f32x4*)(out + off) = o0; *(f32x4*)(out + off + 4) = o1; } }
.Lp6h_16:
	s_nop 3
	v_lshlrev_b32_e32 v240, 16, v232
	v_and_b32_e32 v241, 0xffff0000, v232
	v_lshlrev_b32_e32 v242, 16, v236
	v_and_b32_e32 v243, 0xffff0000, v236
	v_pk_add_f32 v[240:241], v[240:241], v[242:243]
	v_pk_add_f32 v[4:5], v[4:5], v[240:241]
	v_lshlrev_b32_e32 v240, 16, v233
	v_and_b32_e32 v241, 0xffff0000, v233
	v_lshlrev_b32_e32 v242, 16, v237
	v_and_b32_e32 v243, 0xffff0000, v237
	v_pk_add_f32 v[240:241], v[240:241], v[242:243]
	v_pk_add_f32 v[6:7], v[6:7], v[240:241]
	v_lshlrev_b32_e32 v240, 16, v234
	v_and_b32_e32 v241, 0xffff0000, v234
	v_lshlrev_b32_e32 v242, 16, v238
	v_and_b32_e32 v243, 0xffff0000, v238
	v_pk_add_f32 v[240:241], v[240:241], v[242:243]
	v_pk_add_f32 v[0:1], v[0:1], v[240:241]
	v_lshlrev_b32_e32 v240, 16, v235
	v_and_b32_e32 v241, 0xffff0000, v235
	v_lshlrev_b32_e32 v242, 16, v239
	v_and_b32_e32 v243, 0xffff0000, v239
	v_pk_add_f32 v[240:241], v[240:241], v[242:243]
	v_pk_add_f32 v[2:3], v[2:3], v[240:241]
	v_lshl_add_u32 v240, v137, 10, v136
	v_lshlrev_b32_e32 v240, 1, v240
	global_load_dwordx4 v[224:227], v240, s[98:99] offset:256
	global_load_dwordx4 v[228:231], v240, s[100:101] offset:256
	s_branch .Lp6h_ret
.Lp6h_dummy:
	v_lshl_add_u32 v240, v137, 10, v136
	v_lshlrev_b32_e32 v240, 1, v240
	global_load_dwordx4 v[224:227], v240, s[98:99] offset:256
	global_load_dwordx4 v[228:231], v240, s[100:101] offset:256
.Lp6h_ret:
	s_waitcnt vmcnt(10)
	s_waitcnt lgkmcnt(0)
	s_barrier
	s_setprio 1
	s_waitcnt lgkmcnt(0)
	v_mfma_f32_16x16x32_bf16 v[124:127], v[152:155], v[184:187], v[124:127]
	v_mfma_f32_16x16x32_bf16 v[120:123], v[160:163], v[184:187], v[120:123]
	v_mfma_f32_16x16x32_bf16 v[108:111], v[152:155], v[192:195], v[108:111]
	v_mfma_f32_16x16x32_bf16 v[104:107], v[160:163], v[192:195], v[104:107]
	v_mfma_f32_16x16x32_bf16 v[92:95], v[152:155], v[200:203], v[92:95]
	v_mfma_f32_16x16x32_bf16 v[88:91], v[160:163], v[200:203], v[88:91]
	v_mfma_f32_16x16x32_bf16 v[76:79], v[152:155], v[208:211], v[76:79]
	v_mfma_f32_16x16x32_bf16 v[72:75], v[160:163], v[208:211], v[72:75]
	v_mfma_f32_16x16x32_bf16 v[124:127], v[156:159], v[188:191], v[124:127]
	v_mfma_f32_16x16x32_bf16 v[120:123], v[164:167], v[188:191], v[120:123]
	v_mfma_f32_16x16x32_bf16 v[108:111], v[156:159], v[196:199], v[108:111]
	v_mfma_f32_16x16x32_bf16 v[104:107], v[164:167], v[196:199], v[104:107]
	v_mfma_f32_16x16x32_bf16 v[92:95], v[156:159], v[204:207], v[92:95]
	v_mfma_f32_16x16x32_bf16 v[88:91], v[164:167], v[204:207], v[88:91]
	v_mfma_f32_16x16x32_bf16 v[76:79], v[156:159], v[212:215], v[76:79]
	v_mfma_f32_16x16x32_bf16 v[72:75], v[164:167], v[212:215], v[72:75]
	s_setprio 0
	s_setprio 1
	v_mfma_f32_16x16x32_bf16 v[116:119], v[168:171], v[184:187], v[116:119]
	v_mfma_f32_16x16x32_bf16 v[112:115], v[176:179], v[184:187], v[112:115]
	v_mfma_f32_16x16x32_bf16 v[100:103], v[168:171], v[192:195], v[100:103]
	v_mfma_f32_16x16x32_bf16 v[96:99], v[176:179], v[192:195], v[96:99]
	v_mfma_f32_16x16x32_bf16 v[84:87], v[168:171], v[200:203], v[84:87]
	v_mfma_f32_16x16x32_bf16 v[80:83], v[176:179], v[200:203], v[80:83]
	v_mfma_f32_16x16x32_bf16 v[68:71], v[168:171], v[208:211], v[68:71]
	v_mfma_f32_16x16x32_bf16 v[64:67], v[176:179], v[208:211], v[64:67]
	v_mfma_f32_16x16x32_bf16 v[116:119], v[172:175], v[188:191], v[116:119]
	v_mfma_f32_16x16x32_bf16 v[112:115], v[180:183], v[188:191], v[112:115]
	v_mfma_f32_16x16x32_bf16 v[100:103], v[172:175], v[196:199], v[100:103]
	v_mfma_f32_16x16x32_bf16 v[96:99], v[180:183], v[196:199], v[96:99]
	v_mfma_f32_16x16x32_bf16 v[84:87], v[172:175], v[204:207], v[84:87]
	v_mfma_f32_16x16x32_bf16 v[80:83], v[180:183], v[204:207], v[80:83]
	v_mfma_f32_16x16x32_bf16 v[68:71], v[172:175], v[212:215], v[68:71]
	v_mfma_f32_16x16x32_bf16 v[64:67], v[180:183], v[212:215], v[64:67]
	s_setprio 0
	s_barrier
	s_add_i32 s64, s55, s46
	v_lshl_add_u64 v[146:147], s[40:41], 0, v[130:131]
	s_mov_b32 m0, s64
	ds_read_b128 v[184:187], v151 offset:16384
	ds_read_b128 v[188:191], v151 offset:17408
	ds_read_b128 v[192:195], v151 offset:18432
	ds_read_b128 v[196:199], v151 offset:19456
	ds_read_b128 v[200:203], v151 offset:20480
	ds_read_b128 v[204:207], v151 offset:21504
	ds_read_b128 v[208:211], v151 offset:22528
	ds_read_b128 v[212:215], v151 offset:23552
	global_load_lds_dwordx4 v[146:147], off
	s_add_i32 m0, s64, 0x2000
	s_add_u32 s64, s40, 0xb0000
	v_lshl_add_u64 v[216:217], s[40:41], 0, v[134:135]
	s_addc_u32 s65, s41, 0
	s_add_i32 s66, s56, s46
	global_load_lds_dwordx4 v[216:217], off
	v_lshl_add_u64 v[218:219], s[64:65], 0, v[130:131]
	s_mov_b32 m0, s66
	v_lshl_add_u64 v[220:221], s[42:43], 0, v[132:133]
	global_load_lds_dwordx4 v[218:219], off
	v_lshl_add_u64 v[218:219], s[64:65], 0, v[134:135]
	s_add_i32 m0, s66, 0x2000
	s_nop 0
	global_load_lds_dwordx4 v[218:219], off
	v_lshl_add_u64 v[218:219], s[42:43], 0, v[128:129]
	s_mov_b32 m0, s47
	s_nop 0
	global_load_lds_dwordx4 v[218:219], off
	s_mov_b32 m0, s48
	s_nop 0
	global_load_lds_dwordx4 v[220:221], off
	s_waitcnt vmcnt(10)
	s_waitcnt lgkmcnt(0)
	s_barrier
; #define PG8_STAGE(bufoff, gbase, voff) do { _Pragma("unroll") for (int _i = 0; _i < 2; ++_i) \
;         __builtin_amdgcn_global_load_lds((const unsigned*)((const char*)(gbase) + (voff)[_i]), (PG8_LAS unsigned*)(lds + (bufoff) + ldsw + _i * 8192), 16, 0, 0); } while (0)
; #define PG8_LDA(dst, b, h) do { _Pragma("unroll") for (int m = 0; m < 4; ++m) _Pragma("unroll") for (int k = 0; k < 2; ++k) dst[m][k] = *(const PG8_LAS bf16x8*)(lds + PG8_SA(b, h) + aoff + m * 2048 + k * 1024); } while (0)
; #define PG8_LDB(dst, b, h) do { _Pragma("unroll") for (int n = 0; n < 2; ++n) _Pragma("unroll") for (int k = 0; k < 2; ++k) dst[n][k] = *(const PG8_LAS bf16x8*)(lds + PG8_SB(b, h) + boff + n * 2048 + k * 1024); } while (0)
; #define PG8_MMA(ai, bj, At, Bt) do { __builtin_amdgcn_s_setprio(1); _Pragma("unroll") for (int m = 0; m < 4; ++m) _Pragma("unroll") for (int n = 0; n < 2; ++n) _Pragma("unroll") for (int k = 0; k < 2; ++k) \
;         acc[ai][bj][m][n] = __builtin_amdgcn_mfma_f32_16x16x32_bf16(Bt[n][k], At[m][k], acc[ai][bj][m][n], 0, 0, 0); __builtin_amdgcn_s_setprio(0); } while (0)
; #define PG8_WAIT_V(n) asm volatile("s_waitcnt vmcnt(" #n ")" ::: "memory")
; #define PG8_WAIT_L(n) asm volatile("s_waitcnt lgkmcnt(" #n ")" ::: "memory")
; #define PG8_BAR __builtin_amdgcn_s_barrier()
; #define PG8_SCHED __builtin_amdgcn_sched_barrier(0)
; template <class Epi, class Sched, bool ALIGN_EPI>
; __device__ __forceinline__ void gemm_phase(PG8_LAS unsigned char* lds, const Gemm g, const Sched& S, const Epi& E) {
;     ...
;             PG8_WAIT_V(8); PG8_WAIT_L(0); PG8_BAR; PG8_MMA(1, 0, At, B0); PG8_MMA(1, 1, At, B1); PG8_BAR; PG8_SCHED;
;             PG8_LDB(B0, 1, 0); PG8_LDB(B1, 1, 1); PG8_SCHED; PG8_LDA(At, 1, 0); PG8_STAGE(PG8_SA(0, 1), a2 + hsA, voffA);
;             PG8_WAIT_V(8); PG8_WAIT_L(0); PG8_BAR; PG8_MMA(0, 0, At, B0); PG8_MMA(0, 1, At, B1); PG8_BAR; PG8_SCHED;
	s_setprio 1
	s_waitcnt lgkmcnt(0)
	v_mfma_f32_16x16x32_bf16 v[60:63], v[152:155], v[184:187], v[60:63]
	v_mfma_f32_16x16x32_bf16 v[56:59], v[160:163], v[184:187], v[56:59]
	v_mfma_f32_16x16x32_bf16 v[44:47], v[152:155], v[192:195], v[44:47]
	v_mfma_f32_16x16x32_bf16 v[40:43], v[160:163], v[192:195], v[40:43]
	v_mfma_f32_16x16x32_bf16 v[28:31], v[152:155], v[200:203], v[28:31]
	v_mfma_f32_16x16x32_bf16 v[24:27], v[160:163], v[200:203], v[24:27]
	v_mfma_f32_16x16x32_bf16 v[12:15], v[152:155], v[208:211], v[12:15]
	v_mfma_f32_16x16x32_bf16 v[8:11], v[160:163], v[208:211], v[8:11]
	v_mfma_f32_16x16x32_bf16 v[60:63], v[156:159], v[188:191], v[60:63]
	v_mfma_f32_16x16x32_bf16 v[56:59], v[164:167], v[188:191], v[56:59]
	v_mfma_f32_16x16x32_bf16 v[44:47], v[156:159], v[196:199], v[44:47]
	v_mfma_f32_16x16x32_bf16 v[40:43], v[164:167], v[196:199], v[40:43]
	v_mfma_f32_16x16x32_bf16 v[28:31], v[156:159], v[204:207], v[28:31]
	v_mfma_f32_16x16x32_bf16 v[24:27], v[164:167], v[204:207], v[24:27]
	v_mfma_f32_16x16x32_bf16 v[12:15], v[156:159], v[212:215], v[12:15]
	v_mfma_f32_16x16x32_bf16 v[8:11], v[164:167], v[212:215], v[8:11]
	s_setprio 0
	s_setprio 1
	v_mfma_f32_16x16x32_bf16 v[52:55], v[168:171], v[184:187], v[52:55]
	v_mfma_f32_16x16x32_bf16 v[48:51], v[176:179], v[184:187], v[48:51]
	v_mfma_f32_16x16x32_bf16 v[36:39], v[168:171], v[192:195], v[36:39]
	v_mfma_f32_16x16x32_bf16 v[32:35], v[176:179], v[192:195], v[32:35]
	v_mfma_f32_16x16x32_bf16 v[20:23], v[168:171], v[200:203], v[20:23]
	v_mfma_f32_16x16x32_bf16 v[16:19], v[176:179], v[200:203], v[16:19]
	v_mfma_f32_16x16x32_bf16 v[4:7], v[168:171], v[208:211], v[4:7]
	v_mfma_f32_16x16x32_bf16 v[0:3], v[176:179], v[208:211], v[0:3]
	v_mfma_f32_16x16x32_bf16 v[52:55], v[172:175], v[188:191], v[52:55]
	v_mfma_f32_16x16x32_bf16 v[48:51], v[180:183], v[188:191], v[48:51]
	v_mfma_f32_16x16x32_bf16 v[36:39], v[172:175], v[196:199], v[36:39]
	v_mfma_f32_16x16x32_bf16 v[32:35], v[180:183], v[196:199], v[32:35]
	v_mfma_f32_16x16x32_bf16 v[20:23], v[172:175], v[204:207], v[20:23]
	v_mfma_f32_16x16x32_bf16 v[16:19], v[180:183], v[204:207], v[16:19]
	v_mfma_f32_16x16x32_bf16 v[4:7], v[172:175], v[212:215], v[4:7]
	v_mfma_f32_16x16x32_bf16 v[0:3], v[180:183], v[212:215], v[0:3]
	s_setprio 0
	s_barrier
	s_add_i32 s64, 0, 0x18000
	s_add_i32 s65, 0, 0x1c000
	v_add_u32_e32 v164, s64, v148
	v_add_u32_e32 v180, s65, v148
	ds_read_b128 v[152:155], v164
	ds_read_b128 v[156:159], v164 offset:1024
	ds_read_b128 v[160:163], v164 offset:2048
	ds_read_b128 v[164:167], v164 offset:3072
	ds_read_b128 v[168:171], v180
	ds_read_b128 v[172:175], v180 offset:1024
	ds_read_b128 v[176:179], v180 offset:2048
	ds_read_b128 v[180:183], v180 offset:3072
	s_add_u32 s42, s42, 0xb0000
	s_addc_u32 s43, s43, 0
	s_mov_b32 m0, s49
	v_lshl_add_u64 v[222:223], s[42:43], 0, v[128:129]
	ds_read_b128 v[184:187], v151 offset:32768
	ds_read_b128 v[188:191], v151 offset:33792
	ds_read_b128 v[192:195], v151 offset:34816
	ds_read_b128 v[196:199], v151 offset:35840
	ds_read_b128 v[200:203], v151 offset:36864
	ds_read_b128 v[204:207], v151 offset:37888
	ds_read_b128 v[208:211], v151 offset:38912
	ds_read_b128 v[212:215], v151 offset:39936
	global_load_lds_dwordx4 v[222:223], off
	v_lshl_add_u64 v[222:223], s[42:43], 0, v[132:133]
	s_mov_b32 m0, s50
	s_nop 0
	global_load_lds_dwordx4 v[222:223], off
	s_waitcnt vmcnt(10)
	s_waitcnt lgkmcnt(0)
	s_barrier
	s_setprio 1
	s_waitcnt lgkmcnt(0)
	v_mfma_f32_16x16x32_bf16 v[124:127], v[152:155], v[184:187], v[124:127]
	v_mfma_f32_16x16x32_bf16 v[120:123], v[160:163], v[184:187], v[120:123]
	v_mfma_f32_16x16x32_bf16 v[108:111], v[152:155], v[192:195], v[108:111]
	v_mfma_f32_16x16x32_bf16 v[104:107], v[160:163], v[192:195], v[104:107]
	v_mfma_f32_16x16x32_bf16 v[92:95], v[152:155], v[200:203], v[92:95]
	v_mfma_f32_16x16x32_bf16 v[88:91], v[160:163], v[200:203], v[88:91]
	v_mfma_f32_16x16x32_bf16 v[76:79], v[152:155], v[208:211], v[76:79]
	v_mfma_f32_16x16x32_bf16 v[72:75], v[160:163], v[208:211], v[72:75]
	v_mfma_f32_16x16x32_bf16 v[124:127], v[156:159], v[188:191], v[124:127]
	v_mfma_f32_16x16x32_bf16 v[120:123], v[164:167], v[188:191], v[120:123]
	v_mfma_f32_16x16x32_bf16 v[108:111], v[156:159], v[196:199], v[108:111]
	v_mfma_f32_16x16x32_bf16 v[104:107], v[164:167], v[196:199], v[104:107]
	v_mfma_f32_16x16x32_bf16 v[92:95], v[156:159], v[204:207], v[92:95]
	v_mfma_f32_16x16x32_bf16 v[88:91], v[164:167], v[204:207], v[88:91]
	v_mfma_f32_16x16x32_bf16 v[76:79], v[156:159], v[212:215], v[76:79]
	v_mfma_f32_16x16x32_bf16 v[72:75], v[164:167], v[212:215], v[72:75]
	s_setprio 0
	s_setprio 1
	v_mfma_f32_16x16x32_bf16 v[116:119], v[168:171], v[184:187], v[116:119]
	v_mfma_f32_16x16x32_bf16 v[112:115], v[176:179], v[184:187], v[112:115]
	v_mfma_f32_16x16x32_bf16 v[100:103], v[168:171], v[192:195], v[100:103]
	v_mfma_f32_16x16x32_bf16 v[96:99], v[176:179], v[192:195], v[96:99]
	v_mfma_f32_16x16x32_bf16 v[84:87], v[168:171], v[200:203], v[84:87]
	v_mfma_f32_16x16x32_bf16 v[80:83], v[176:179], v[200:203], v[80:83]
	v_mfma_f32_16x16x32_bf16 v[68:71], v[168:171], v[208:211], v[68:71]
	v_mfma_f32_16x16x32_bf16 v[64:67], v[176:179], v[208:211], v[64:67]
	v_mfma_f32_16x16x32_bf16 v[116:119], v[172:175], v[188:191], v[116:119]
	v_mfma_f32_16x16x32_bf16 v[112:115], v[180:183], v[188:191], v[112:115]
	v_mfma_f32_16x16x32_bf16 v[100:103], v[172:175], v[196:199], v[100:103]
	v_mfma_f32_16x16x32_bf16 v[96:99], v[180:183], v[196:199], v[96:99]
	v_mfma_f32_16x16x32_bf16 v[84:87], v[172:175], v[204:207], v[84:87]
	v_mfma_f32_16x16x32_bf16 v[80:83], v[180:183], v[204:207], v[80:83]
	v_mfma_f32_16x16x32_bf16 v[68:71], v[172:175], v[212:215], v[68:71]
	v_mfma_f32_16x16x32_bf16 v[64:67], v[180:183], v[212:215], v[64:67]
	s_setprio 0
	s_barrier
; __device__ __forceinline__ float bflo(unsigned w) { return __uint_as_float(w << 16); }
; __device__ __forceinline__ float bfhi(unsigned w) { return __uint_as_float(w & 0xffff0000u); }
; #define PG8_STAGE(bufoff, gbase, voff) do { _Pragma("unroll") for (int _i = 0; _i < 2; ++_i) \
;         __builtin_amdgcn_global_load_lds((const unsigned*)((const char*)(gbase) + (voff)[_i]), (PG8_LAS unsigned*)(lds + (bufoff) + ldsw + _i * 8192), 16, 0, 0); } while (0)
; #define PG8_BAR __builtin_amdgcn_s_barrier()
; template <class Epi, class Sched, bool ALIGN_EPI>
; __device__ __forceinline__ void gemm_phase(PG8_LAS unsigned char* lds, const Gemm g, const Sched& S, const Epi& E) {
;     ...
;             PG8_LDA(At, 1, 1); PG8_STAGE(PG8_SB(1, 0), b3, voffB); PG8_STAGE(PG8_SB(1, 1), b3 + hsB, voffB); PG8_STAGE(PG8_SA(1, 0), a3, voffA);
;             PG8_WAIT_V(8); PG8_WAIT_L(0); PG8_BAR; PG8_MMA(1, 0, At, B0); PG8_MMA(1, 1, At, B1); PG8_BAR; PG8_SCHED;
;         }
;         if constexpr (ALIGN_EPI) { if (wr == 0) PG8_BAR; }
;         E(acc, cur, wr, wc, fr, fq);
;         if (!has_next) break;
;     __device__ __forceinline__ void operator()(const f32x4 (&acc)[2][2][4][2], const Unit& u, int wr, int wc, int fr, int fq) const {
;         int row0 = u.pm * BM + wr * 64 + fr; asm volatile("" : "+v"(row0));
; #pragma unroll
;         for (int ai = 0; ai < 2; ++ai)
; #pragma unroll
;             for (int m = 0; m < 4; ++m) { const int row = row0 + ai * HALF + m * 16;
; #pragma unroll
;                 for (int bj = 0; bj < 2; ++bj) { const size_t off = (size_t)row * DM + u.pn * BM + bj * HALF + wc * 32 + 8 * fq;
;                     const u32x4 hw = *(const u32x4*)(H1B + off), lw = *(const u32x4*)(LO + off);
;                     f32x4 o0, o1;
;                     o0[0] = (bflo(hw.x) + bflo(lw.x)) + acc[ai][bj][m][0][0]; o0[1] = (bfhi(hw.x) + bfhi(lw.x)) + acc[ai][bj][m][0][1];
;                     o0[2] = (bflo(hw.y) + bflo(lw.y)) + acc[ai][bj][m][0][2]; o0[3] = (bfhi(hw.y) + bfhi(lw.y)) + acc[ai][bj][m][0][3];
;                     o1[0] = (bflo(hw.z) + bflo(lw.z)) + acc[ai][bj][m][1][0]; o1[1] = (bfhi(hw.z) + bfhi(lw.z)) + acc[ai][bj][m][1][1];
;                     o1[2] = (bflo(hw.w) + bflo(lw.w)) + acc[ai][bj][m][1][2]; o1[3] = (bfhi(hw.w) + bfhi(lw.w)) + acc[ai][bj][m][1][3];
;                     *(f32x4*)(out + off) = o0; *(f32x4*)(out + off + 4) = o1; } }
;     }
	s_add_i32 s42, s64, s46
	v_lshl_add_u64 v[146:147], v[146:147], 0, s[10:11]
	s_mov_b32 m0, s42
	ds_read_b128 v[184:187], v151 offset:49152
	ds_read_b128 v[188:191], v151 offset:50176
	ds_read_b128 v[192:195], v151 offset:51200
	ds_read_b128 v[196:199], v151 offset:52224
	ds_read_b128 v[200:203], v151 offset:53248
	ds_read_b128 v[204:207], v151 offset:54272
	ds_read_b128 v[208:211], v151 offset:55296
	ds_read_b128 v[212:215], v151 offset:56320
	global_load_lds_dwordx4 v[146:147], off
	s_add_i32 m0, s42, 0x2000
	s_add_u32 s40, s40, 0xb0080
	v_lshl_add_u64 v[146:147], v[216:217], 0, s[10:11]
	s_addc_u32 s41, s41, 0
	s_add_i32 s42, s65, s46
	global_load_lds_dwordx4 v[146:147], off
	v_lshl_add_u64 v[146:147], s[40:41], 0, v[130:131]
	s_mov_b32 m0, s42
	s_nop 0
	global_load_lds_dwordx4 v[146:147], off
	v_lshl_add_u64 v[146:147], s[40:41], 0, v[134:135]
	s_add_i32 m0, s42, 0x2000
	s_nop 0
	global_load_lds_dwordx4 v[146:147], off
	v_lshl_add_u64 v[146:147], v[218:219], 0, s[10:11]
	s_mov_b32 m0, s52
	s_nop 0
	global_load_lds_dwordx4 v[146:147], off
	v_lshl_add_u64 v[146:147], v[220:221], 0, s[10:11]
	s_mov_b32 m0, s53
	s_nop 0
	global_load_lds_dwordx4 v[146:147], off
	s_waitcnt vmcnt(8)
	s_waitcnt lgkmcnt(0)
	s_barrier
	s_setprio 1
	s_waitcnt lgkmcnt(0)
	v_mfma_f32_16x16x32_bf16 v[60:63], v[152:155], v[184:187], v[60:63]
	v_mfma_f32_16x16x32_bf16 v[56:59], v[160:163], v[184:187], v[56:59]
	v_mfma_f32_16x16x32_bf16 v[44:47], v[152:155], v[192:195], v[44:47]
	v_mfma_f32_16x16x32_bf16 v[40:43], v[160:163], v[192:195], v[40:43]
	v_mfma_f32_16x16x32_bf16 v[28:31], v[152:155], v[200:203], v[28:31]
	v_mfma_f32_16x16x32_bf16 v[24:27], v[160:163], v[200:203], v[24:27]
	v_mfma_f32_16x16x32_bf16 v[12:15], v[152:155], v[208:211], v[12:15]
	v_mfma_f32_16x16x32_bf16 v[8:11], v[160:163], v[208:211], v[8:11]
	v_mfma_f32_16x16x32_bf16 v[60:63], v[156:159], v[188:191], v[60:63]
	v_mfma_f32_16x16x32_bf16 v[56:59], v[164:167], v[188:191], v[56:59]
	v_mfma_f32_16x16x32_bf16 v[44:47], v[156:159], v[196:199], v[44:47]
	v_mfma_f32_16x16x32_bf16 v[40:43], v[164:167], v[196:199], v[40:43]
	v_mfma_f32_16x16x32_bf16 v[28:31], v[156:159], v[204:207], v[28:31]
	v_mfma_f32_16x16x32_bf16 v[24:27], v[164:167], v[204:207], v[24:27]
	v_mfma_f32_16x16x32_bf16 v[12:15], v[156:159], v[212:215], v[12:15]
	v_mfma_f32_16x16x32_bf16 v[8:11], v[164:167], v[212:215], v[8:11]
	s_setprio 0
	s_setprio 1
	v_mfma_f32_16x16x32_bf16 v[52:55], v[168:171], v[184:187], v[52:55]
	v_mfma_f32_16x16x32_bf16 v[48:51], v[176:179], v[184:187], v[48:51]
	v_mfma_f32_16x16x32_bf16 v[36:39], v[168:171], v[192:195], v[36:39]
	v_mfma_f32_16x16x32_bf16 v[32:35], v[176:179], v[192:195], v[32:35]
	v_mfma_f32_16x16x32_bf16 v[20:23], v[168:171], v[200:203], v[20:23]
	v_mfma_f32_16x16x32_bf16 v[16:19], v[176:179], v[200:203], v[16:19]
	v_mfma_f32_16x16x32_bf16 v[4:7], v[168:171], v[208:211], v[4:7]
	v_mfma_f32_16x16x32_bf16 v[0:3], v[176:179], v[208:211], v[0:3]
	v_mfma_f32_16x16x32_bf16 v[52:55], v[172:175], v[188:191], v[52:55]
	v_mfma_f32_16x16x32_bf16 v[48:51], v[180:183], v[188:191], v[48:51]
	v_mfma_f32_16x16x32_bf16 v[36:39], v[172:175], v[196:199], v[36:39]
	v_mfma_f32_16x16x32_bf16 v[32:35], v[180:183], v[196:199], v[32:35]
	v_mfma_f32_16x16x32_bf16 v[20:23], v[172:175], v[204:207], v[20:23]
	v_mfma_f32_16x16x32_bf16 v[16:19], v[180:183], v[204:207], v[16:19]
	v_mfma_f32_16x16x32_bf16 v[4:7], v[172:175], v[212:215], v[4:7]
	v_mfma_f32_16x16x32_bf16 v[0:3], v[180:183], v[212:215], v[0:3]
	s_setprio 0
	s_barrier
	s_add_i32 s63, s63, 2
	s_add_u32 s38, s38, 0x100
	s_addc_u32 s39, s39, 0
	s_add_u32 s61, s61, 0x100
	s_addc_u32 s62, s62, 0
	s_cmp_gt_u32 s63, 41
	s_cbranch_scc0 .LBB0_1025
	s_and_b64 vcc, exec, s[12:13]
	s_cbranch_vccz .LBB0_1028
	s_barrier
.LBB0_1028:
	v_lshl_add_u32 v146, s59, 8, v137
	s_lshl_b32 s38, s60, 8
	v_or_b32_e32 v147, s38, v136
	v_lshl_add_u32 v146, v146, 10, v147
	v_lshlrev_b32_e32 v147, 2, v146
	s_mov_b64 s[14:15], s[20:21]
	global_store_dwordx4 v147, v[124:127], s[14:15]
	global_store_dwordx4 v147, v[120:123], s[14:15] offset:16
	global_store_dwordx4 v147, v[116:119], s[14:15] offset:512
	global_store_dwordx4 v147, v[112:115], s[14:15] offset:528
	s_add_u32 s14, s20, 0x10000
	s_addc_u32 s15, s21, 0
	global_store_dwordx4 v147, v[108:111], s[14:15]
	global_store_dwordx4 v147, v[104:107], s[14:15] offset:16
	global_store_dwordx4 v147, v[100:103], s[14:15] offset:512
	global_store_dwordx4 v147, v[96:99], s[14:15] offset:528
	s_add_u32 s14, s20, 0x20000
	s_addc_u32 s15, s21, 0
	global_store_dwordx4 v147, v[92:95], s[14:15]
	global_store_dwordx4 v147, v[88:91], s[14:15] offset:16
	global_store_dwordx4 v147, v[84:87], s[14:15] offset:512
	global_store_dwordx4 v147, v[80:83], s[14:15] offset:528
	s_add_u32 s14, s20, 0x30000
	s_addc_u32 s15, s21, 0
	global_store_dwordx4 v147, v[76:79], s[14:15]
	global_store_dwordx4 v147, v[72:75], s[14:15] offset:16
	global_store_dwordx4 v147, v[68:71], s[14:15] offset:512
	global_store_dwordx4 v147, v[64:67], s[14:15] offset:528
	s_add_u32 s14, s20, 0x80000
	s_addc_u32 s15, s21, 0
	global_store_dwordx4 v147, v[60:63], s[14:15]
	global_store_dwordx4 v147, v[56:59], s[14:15] offset:16
	global_store_dwordx4 v147, v[52:55], s[14:15] offset:512
	global_store_dwordx4 v147, v[48:51], s[14:15] offset:528
	s_add_u32 s14, s20, 0x90000
	s_addc_u32 s15, s21, 0
	global_store_dwordx4 v147, v[44:47], s[14:15]
	global_store_dwordx4 v147, v[40:43], s[14:15] offset:16
	global_store_dwordx4 v147, v[36:39], s[14:15] offset:512
	global_store_dwordx4 v147, v[32:35], s[14:15] offset:528
	s_add_u32 s14, s20, 0xa0000
	s_addc_u32 s15, s21, 0
	global_store_dwordx4 v147, v[28:31], s[14:15]
	global_store_dwordx4 v147, v[24:27], s[14:15] offset:16
	global_store_dwordx4 v147, v[20:23], s[14:15] offset:512
	global_store_dwordx4 v147, v[16:19], s[14:15] offset:528
	s_add_u32 s14, s20, 0xb0000
	s_addc_u32 s15, s21, 0
	global_store_dwordx4 v147, v[12:15], s[14:15]
	global_store_dwordx4 v147, v[8:11], s[14:15] offset:16
	global_store_dwordx4 v147, v[4:7], s[14:15] offset:512
	global_store_dwordx4 v147, v[0:3], s[14:15] offset:528
	s_and_b64 vcc, exec, s[0:1]
	s_mov_b64 s[0:1], -1
	s_cbranch_vccnz .LBB0_1013
	s_andn2_b64 vcc, exec, s[4:5]
	s_cbranch_vccnz .LBB0_1012
	s_barrier
	s_branch .LBB0_1012
